# P2 k-loop: same SGPR-base LDS-DMA + pipelined LDS operand reads as P8/P10
# speedup vs baseline: 1.0265x; 1.0002x over previous
.LBB0_376:
	s_ashr_i32 s17, s16, 31
	v_cmp_lt_i64_e32 vcc, s[20:21], v[140:141]
	s_lshl_b64 s[20:21], s[16:17], 20
	s_add_u32 s20, s35, s20
	s_addc_u32 s21, s36, s21
	s_and_b64 s[22:23], vcc, exec
	s_cselect_b32 s17, s21, s25
	s_cselect_b32 s19, s20, s24
	s_ashr_i32 s15, s14, 31
	s_lshl_b64 s[22:23], s[14:15], 20
	s_add_u32 s22, s37, s22
	s_addc_u32 s23, s38, s23
	s_and_b64 s[28:29], vcc, exec
	s_cselect_b32 s15, s23, s27
	s_cselect_b32 s51, s22, s26
	s_add_u32 s24, s24, 0x80080
	s_addc_u32 s25, s25, 0
	s_add_u32 s52, s26, 0x100
	s_addc_u32 s53, s27, 0
	s_mov_b32 s54, -2
	v_add_u32_e32 v222, 0x18000, v147
	v_add_u32_e32 v223, 0x1c000, v147
	ds_read_b128 v[152:155], v149
	ds_read_b128 v[156:159], v149 offset:1024
	ds_read_b128 v[160:163], v149 offset:2048
	ds_read_b128 v[168:171], v149 offset:3072
	ds_read_b128 v[172:175], v150
	ds_read_b128 v[176:179], v150 offset:1024
	ds_read_b128 v[180:183], v150 offset:2048
	ds_read_b128 v[184:187], v150 offset:3072
	ds_read_b128 v[188:191], v150 offset:4096
	ds_read_b128 v[192:195], v150 offset:5120
	ds_read_b128 v[196:199], v150 offset:6144
	ds_read_b128 v[200:203], v150 offset:7168
	s_add_u32 s26, s24, 0xfff80080
	s_addc_u32 s27, s25, -1
	s_cmp_eq_u32 s54, 28
	s_cselect_b32 s29, s17, s27
	s_cselect_b32 s28, s19, s26
	s_cselect_b32 s27, s15, s53
	s_cselect_b32 s26, s51, s52
	s_add_i32 m0, s39, 0xc000
	s_nop 0
	global_load_lds_dwordx4 v136, s[24:25]
	s_add_i32 m0, s39, 0xe000
	s_nop 0
	global_load_lds_dwordx4 v138, s[24:25]
	s_waitcnt vmcnt(10)
	s_barrier
	s_waitcnt lgkmcnt(0)
	s_setprio 1
	v_mfma_f32_16x16x32_bf16 v[126:129], v[152:155], v[172:175], 0
	ds_read_b128 v[204:207], v151
	v_mfma_f32_16x16x32_bf16 v[122:125], v[160:163], v[172:175], 0
	v_mfma_f32_16x16x32_bf16 v[118:121], v[152:155], v[180:183], 0
	v_mfma_f32_16x16x32_bf16 v[114:117], v[160:163], v[180:183], 0
	v_mfma_f32_16x16x32_bf16 v[102:105], v[152:155], v[188:191], 0
	ds_read_b128 v[208:211], v151 offset:1024
	v_mfma_f32_16x16x32_bf16 v[98:101], v[160:163], v[188:191], 0
	v_mfma_f32_16x16x32_bf16 v[86:89], v[152:155], v[196:199], 0
	v_mfma_f32_16x16x32_bf16 v[82:85], v[160:163], v[196:199], 0
	v_mfma_f32_16x16x32_bf16 v[126:129], v[156:159], v[176:179], v[126:129]
	ds_read_b128 v[212:215], v151 offset:2048
	v_mfma_f32_16x16x32_bf16 v[122:125], v[168:171], v[176:179], v[122:125]
	v_mfma_f32_16x16x32_bf16 v[118:121], v[156:159], v[184:187], v[118:121]
	v_mfma_f32_16x16x32_bf16 v[114:117], v[168:171], v[184:187], v[114:117]
	v_mfma_f32_16x16x32_bf16 v[102:105], v[156:159], v[192:195], v[102:105]
	ds_read_b128 v[216:219], v151 offset:3072
	v_mfma_f32_16x16x32_bf16 v[98:101], v[168:171], v[192:195], v[98:101]
	v_mfma_f32_16x16x32_bf16 v[86:89], v[156:159], v[200:203], v[86:89]
	v_mfma_f32_16x16x32_bf16 v[82:85], v[168:171], v[200:203], v[82:85]
	s_setprio 0
	s_barrier
	s_add_i32 s55, s47, s34
	s_add_u32 s96, s26, 0x80
	s_addc_u32 s97, s27, 0
	s_mov_b32 m0, s55
	s_nop 0
	global_load_lds_dwordx4 v130, s[26:27]
	s_add_i32 m0, s55, 0x2000
	s_nop 0
	global_load_lds_dwordx4 v132, s[26:27]
	s_waitcnt vmcnt(10)
	s_barrier
	s_waitcnt lgkmcnt(0)
	s_setprio 1
	v_mfma_f32_16x16x32_bf16 v[110:113], v[204:207], v[172:175], 0
	ds_read_b128 v[224:227], v150 offset:16384
	v_mfma_f32_16x16x32_bf16 v[106:109], v[212:215], v[172:175], 0
	v_mfma_f32_16x16x32_bf16 v[94:97], v[204:207], v[180:183], 0
	ds_read_b128 v[228:231], v150 offset:17408
	v_mfma_f32_16x16x32_bf16 v[90:93], v[212:215], v[180:183], 0
	v_mfma_f32_16x16x32_bf16 v[78:81], v[204:207], v[188:191], 0
	ds_read_b128 v[232:235], v150 offset:18432
	v_mfma_f32_16x16x32_bf16 v[74:77], v[212:215], v[188:191], 0
	v_mfma_f32_16x16x32_bf16 v[70:73], v[204:207], v[196:199], 0
	ds_read_b128 v[236:239], v150 offset:19456
	v_mfma_f32_16x16x32_bf16 v[66:69], v[212:215], v[196:199], 0
	v_mfma_f32_16x16x32_bf16 v[110:113], v[208:211], v[176:179], v[110:113]
	ds_read_b128 v[240:243], v150 offset:20480
	v_mfma_f32_16x16x32_bf16 v[106:109], v[216:219], v[176:179], v[106:109]
	v_mfma_f32_16x16x32_bf16 v[94:97], v[208:211], v[184:187], v[94:97]
	ds_read_b128 v[244:247], v150 offset:21504
	v_mfma_f32_16x16x32_bf16 v[90:93], v[216:219], v[184:187], v[90:93]
	v_mfma_f32_16x16x32_bf16 v[78:81], v[208:211], v[192:195], v[78:81]
	ds_read_b128 v[248:251], v150 offset:22528
	v_mfma_f32_16x16x32_bf16 v[74:77], v[216:219], v[192:195], v[74:77]
	v_mfma_f32_16x16x32_bf16 v[70:73], v[208:211], v[200:203], v[70:73]
	ds_read_b128 v[164:167], v150 offset:23552
	v_mfma_f32_16x16x32_bf16 v[66:69], v[216:219], v[200:203], v[66:69]
	s_setprio 0
	s_barrier
	s_mov_b32 m0, s39
	s_add_u32 s94, s28, 0x80
	s_addc_u32 s95, s29, 0
	global_load_lds_dwordx4 v130, s[28:29]
	s_mov_b32 m0, s40
	s_nop 0
	global_load_lds_dwordx4 v132, s[28:29]
	s_waitcnt vmcnt(8)
	s_barrier
	s_waitcnt lgkmcnt(0)
	s_setprio 1
	v_mfma_f32_16x16x32_bf16 v[62:65], v[152:155], v[224:227], 0
	ds_read_b128 v[172:175], v150 offset:32768
	v_mfma_f32_16x16x32_bf16 v[58:61], v[160:163], v[224:227], 0
	v_mfma_f32_16x16x32_bf16 v[54:57], v[152:155], v[232:235], 0
	ds_read_b128 v[176:179], v150 offset:33792
	v_mfma_f32_16x16x32_bf16 v[50:53], v[160:163], v[232:235], 0
	v_mfma_f32_16x16x32_bf16 v[38:41], v[152:155], v[240:243], 0
	ds_read_b128 v[180:183], v150 offset:34816
	v_mfma_f32_16x16x32_bf16 v[34:37], v[160:163], v[240:243], 0
	v_mfma_f32_16x16x32_bf16 v[22:25], v[152:155], v[248:251], 0
	ds_read_b128 v[184:187], v150 offset:35840
	v_mfma_f32_16x16x32_bf16 v[18:21], v[160:163], v[248:251], 0
	v_mfma_f32_16x16x32_bf16 v[62:65], v[156:159], v[228:231], v[62:65]
	ds_read_b128 v[188:191], v150 offset:36864
	v_mfma_f32_16x16x32_bf16 v[58:61], v[168:171], v[228:231], v[58:61]
	v_mfma_f32_16x16x32_bf16 v[54:57], v[156:159], v[236:239], v[54:57]
	ds_read_b128 v[192:195], v150 offset:37888
	v_mfma_f32_16x16x32_bf16 v[50:53], v[168:171], v[236:239], v[50:53]
	v_mfma_f32_16x16x32_bf16 v[38:41], v[156:159], v[244:247], v[38:41]
	ds_read_b128 v[196:199], v150 offset:38912
	v_mfma_f32_16x16x32_bf16 v[34:37], v[168:171], v[244:247], v[34:37]
	v_mfma_f32_16x16x32_bf16 v[22:25], v[156:159], v[164:167], v[22:25]
	ds_read_b128 v[200:203], v150 offset:39936
	v_mfma_f32_16x16x32_bf16 v[18:21], v[168:171], v[164:167], v[18:21]
	s_setprio 0
	s_barrier
	s_add_u32 s56, s26, 0x80000
	s_addc_u32 s57, s27, 0
	s_add_i32 s55, s48, s34
	s_mov_b32 m0, s55
	s_nop 0
	global_load_lds_dwordx4 v130, s[56:57]
	s_add_i32 m0, s55, 0x2000
	s_nop 0
	global_load_lds_dwordx4 v132, s[56:57]
	s_waitcnt vmcnt(10)
	s_barrier
	s_waitcnt lgkmcnt(0)
	s_setprio 1
	v_mfma_f32_16x16x32_bf16 v[46:49], v[204:207], v[224:227], 0
	ds_read_b128 v[152:155], v222
	v_mfma_f32_16x16x32_bf16 v[42:45], v[212:215], v[224:227], 0
	v_mfma_f32_16x16x32_bf16 v[30:33], v[204:207], v[232:235], 0
	v_mfma_f32_16x16x32_bf16 v[26:29], v[212:215], v[232:235], 0
	v_mfma_f32_16x16x32_bf16 v[14:17], v[204:207], v[240:243], 0
	ds_read_b128 v[156:159], v222 offset:1024
	v_mfma_f32_16x16x32_bf16 v[10:13], v[212:215], v[240:243], 0
	v_mfma_f32_16x16x32_bf16 v[6:9], v[204:207], v[248:251], 0
	v_mfma_f32_16x16x32_bf16 v[2:5], v[212:215], v[248:251], 0
	v_mfma_f32_16x16x32_bf16 v[46:49], v[208:211], v[228:231], v[46:49]
	ds_read_b128 v[160:163], v222 offset:2048
	v_mfma_f32_16x16x32_bf16 v[42:45], v[216:219], v[228:231], v[42:45]
	v_mfma_f32_16x16x32_bf16 v[30:33], v[208:211], v[236:239], v[30:33]
	v_mfma_f32_16x16x32_bf16 v[26:29], v[216:219], v[236:239], v[26:29]
	v_mfma_f32_16x16x32_bf16 v[14:17], v[208:211], v[244:247], v[14:17]
	ds_read_b128 v[168:171], v222 offset:3072
	v_mfma_f32_16x16x32_bf16 v[10:13], v[216:219], v[244:247], v[10:13]
	v_mfma_f32_16x16x32_bf16 v[6:9], v[208:211], v[164:167], v[6:9]
	v_mfma_f32_16x16x32_bf16 v[2:5], v[216:219], v[164:167], v[2:5]
	s_setprio 0
	s_barrier
	s_add_i32 s55, 0, 0x18000
	s_add_u32 s28, s28, 0x80000
	s_addc_u32 s29, s29, 0
	s_mov_b32 m0, s41
	s_nop 0
	global_load_lds_dwordx4 v130, s[28:29]
	s_mov_b32 m0, s42
	s_nop 0
	global_load_lds_dwordx4 v132, s[28:29]
	s_waitcnt vmcnt(10)
	s_barrier
	s_waitcnt lgkmcnt(0)
	s_setprio 1
	v_mfma_f32_16x16x32_bf16 v[126:129], v[152:155], v[172:175], v[126:129]
	ds_read_b128 v[204:207], v223
	v_mfma_f32_16x16x32_bf16 v[122:125], v[160:163], v[172:175], v[122:125]
	v_mfma_f32_16x16x32_bf16 v[118:121], v[152:155], v[180:183], v[118:121]
	v_mfma_f32_16x16x32_bf16 v[114:117], v[160:163], v[180:183], v[114:117]
	v_mfma_f32_16x16x32_bf16 v[102:105], v[152:155], v[188:191], v[102:105]
	ds_read_b128 v[208:211], v223 offset:1024
	v_mfma_f32_16x16x32_bf16 v[98:101], v[160:163], v[188:191], v[98:101]
	v_mfma_f32_16x16x32_bf16 v[86:89], v[152:155], v[196:199], v[86:89]
	v_mfma_f32_16x16x32_bf16 v[82:85], v[160:163], v[196:199], v[82:85]
	v_mfma_f32_16x16x32_bf16 v[126:129], v[156:159], v[176:179], v[126:129]
	ds_read_b128 v[212:215], v223 offset:2048
	v_mfma_f32_16x16x32_bf16 v[122:125], v[168:171], v[176:179], v[122:125]
	v_mfma_f32_16x16x32_bf16 v[118:121], v[156:159], v[184:187], v[118:121]
	v_mfma_f32_16x16x32_bf16 v[114:117], v[168:171], v[184:187], v[114:117]
	v_mfma_f32_16x16x32_bf16 v[102:105], v[156:159], v[192:195], v[102:105]
	ds_read_b128 v[216:219], v223 offset:3072
	v_mfma_f32_16x16x32_bf16 v[98:101], v[168:171], v[192:195], v[98:101]
	v_mfma_f32_16x16x32_bf16 v[86:89], v[156:159], v[200:203], v[86:89]
	v_mfma_f32_16x16x32_bf16 v[82:85], v[168:171], v[200:203], v[82:85]
	s_setprio 0
	s_barrier
	s_add_i32 s84, 0, 0x1c000
	s_add_i32 s85, s55, s34
	s_mov_b32 m0, s85
	s_nop 0
	global_load_lds_dwordx4 v130, s[96:97]
	s_add_i32 m0, s85, 0x2000
	s_nop 0
	global_load_lds_dwordx4 v132, s[96:97]
	s_waitcnt vmcnt(10)
	s_barrier
	s_waitcnt lgkmcnt(0)
	s_setprio 1
	v_mfma_f32_16x16x32_bf16 v[110:113], v[204:207], v[172:175], v[110:113]
	ds_read_b128 v[224:227], v150 offset:49152
	v_mfma_f32_16x16x32_bf16 v[106:109], v[212:215], v[172:175], v[106:109]
	v_mfma_f32_16x16x32_bf16 v[94:97], v[204:207], v[180:183], v[94:97]
	ds_read_b128 v[228:231], v150 offset:50176
	v_mfma_f32_16x16x32_bf16 v[90:93], v[212:215], v[180:183], v[90:93]
	v_mfma_f32_16x16x32_bf16 v[78:81], v[204:207], v[188:191], v[78:81]
	ds_read_b128 v[232:235], v150 offset:51200
	v_mfma_f32_16x16x32_bf16 v[74:77], v[212:215], v[188:191], v[74:77]
	v_mfma_f32_16x16x32_bf16 v[70:73], v[204:207], v[196:199], v[70:73]
	ds_read_b128 v[236:239], v150 offset:52224
	v_mfma_f32_16x16x32_bf16 v[66:69], v[212:215], v[196:199], v[66:69]
	v_mfma_f32_16x16x32_bf16 v[110:113], v[208:211], v[176:179], v[110:113]
	ds_read_b128 v[240:243], v150 offset:53248
	v_mfma_f32_16x16x32_bf16 v[106:109], v[216:219], v[176:179], v[106:109]
	v_mfma_f32_16x16x32_bf16 v[94:97], v[208:211], v[184:187], v[94:97]
	ds_read_b128 v[244:247], v150 offset:54272
	v_mfma_f32_16x16x32_bf16 v[90:93], v[216:219], v[184:187], v[90:93]
	v_mfma_f32_16x16x32_bf16 v[78:81], v[208:211], v[192:195], v[78:81]
	ds_read_b128 v[248:251], v150 offset:55296
	v_mfma_f32_16x16x32_bf16 v[74:77], v[216:219], v[192:195], v[74:77]
	v_mfma_f32_16x16x32_bf16 v[70:73], v[208:211], v[200:203], v[70:73]
	ds_read_b128 v[164:167], v150 offset:56320
	v_mfma_f32_16x16x32_bf16 v[66:69], v[216:219], v[200:203], v[66:69]
	s_setprio 0
	s_barrier
	s_mov_b32 m0, s45
	s_nop 0
	global_load_lds_dwordx4 v130, s[94:95]
	s_mov_b32 m0, s46
	s_nop 0
	global_load_lds_dwordx4 v132, s[94:95]
	s_waitcnt vmcnt(8)
	s_barrier
	s_waitcnt lgkmcnt(0)
	s_setprio 1
	v_mfma_f32_16x16x32_bf16 v[62:65], v[152:155], v[224:227], v[62:65]
	ds_read_b128 v[172:175], v150
	v_mfma_f32_16x16x32_bf16 v[58:61], v[160:163], v[224:227], v[58:61]
	v_mfma_f32_16x16x32_bf16 v[54:57], v[152:155], v[232:235], v[54:57]
	ds_read_b128 v[176:179], v150 offset:1024
	v_mfma_f32_16x16x32_bf16 v[50:53], v[160:163], v[232:235], v[50:53]
	v_mfma_f32_16x16x32_bf16 v[38:41], v[152:155], v[240:243], v[38:41]
	ds_read_b128 v[180:183], v150 offset:2048
	v_mfma_f32_16x16x32_bf16 v[34:37], v[160:163], v[240:243], v[34:37]
	v_mfma_f32_16x16x32_bf16 v[22:25], v[152:155], v[248:251], v[22:25]
	ds_read_b128 v[184:187], v150 offset:3072
	v_mfma_f32_16x16x32_bf16 v[18:21], v[160:163], v[248:251], v[18:21]
	v_mfma_f32_16x16x32_bf16 v[62:65], v[156:159], v[228:231], v[62:65]
	ds_read_b128 v[188:191], v150 offset:4096
	v_mfma_f32_16x16x32_bf16 v[58:61], v[168:171], v[228:231], v[58:61]
	v_mfma_f32_16x16x32_bf16 v[54:57], v[156:159], v[236:239], v[54:57]
	ds_read_b128 v[192:195], v150 offset:5120
	v_mfma_f32_16x16x32_bf16 v[50:53], v[168:171], v[236:239], v[50:53]
	v_mfma_f32_16x16x32_bf16 v[38:41], v[156:159], v[244:247], v[38:41]
	ds_read_b128 v[196:199], v150 offset:6144
	v_mfma_f32_16x16x32_bf16 v[34:37], v[168:171], v[244:247], v[34:37]
	v_mfma_f32_16x16x32_bf16 v[22:25], v[156:159], v[164:167], v[22:25]
	ds_read_b128 v[200:203], v150 offset:7168
	v_mfma_f32_16x16x32_bf16 v[18:21], v[168:171], v[164:167], v[18:21]
	s_setprio 0
	s_barrier
	s_add_u32 s26, s26, 0x80080
	s_addc_u32 s27, s27, 0
	s_add_i32 s84, s84, s34
	s_mov_b32 m0, s84
	s_nop 0
	global_load_lds_dwordx4 v130, s[26:27]
	s_add_i32 m0, s84, 0x2000
	s_nop 0
	global_load_lds_dwordx4 v132, s[26:27]
	s_waitcnt vmcnt(10)
	s_barrier
	s_waitcnt lgkmcnt(0)
	s_setprio 1
	v_mfma_f32_16x16x32_bf16 v[46:49], v[204:207], v[224:227], v[46:49]
	ds_read_b128 v[152:155], v149
	v_mfma_f32_16x16x32_bf16 v[42:45], v[212:215], v[224:227], v[42:45]
	v_mfma_f32_16x16x32_bf16 v[30:33], v[204:207], v[232:235], v[30:33]
	v_mfma_f32_16x16x32_bf16 v[26:29], v[212:215], v[232:235], v[26:29]
	v_mfma_f32_16x16x32_bf16 v[14:17], v[204:207], v[240:243], v[14:17]
	ds_read_b128 v[156:159], v149 offset:1024
	v_mfma_f32_16x16x32_bf16 v[10:13], v[212:215], v[240:243], v[10:13]
	v_mfma_f32_16x16x32_bf16 v[6:9], v[204:207], v[248:251], v[6:9]
	v_mfma_f32_16x16x32_bf16 v[2:5], v[212:215], v[248:251], v[2:5]
	v_mfma_f32_16x16x32_bf16 v[46:49], v[208:211], v[228:231], v[46:49]
	ds_read_b128 v[160:163], v149 offset:2048
	v_mfma_f32_16x16x32_bf16 v[42:45], v[216:219], v[228:231], v[42:45]
	v_mfma_f32_16x16x32_bf16 v[30:33], v[208:211], v[236:239], v[30:33]
	v_mfma_f32_16x16x32_bf16 v[26:29], v[216:219], v[236:239], v[26:29]
	v_mfma_f32_16x16x32_bf16 v[14:17], v[208:211], v[244:247], v[14:17]
	ds_read_b128 v[168:171], v149 offset:3072
	v_mfma_f32_16x16x32_bf16 v[10:13], v[216:219], v[244:247], v[10:13]
	v_mfma_f32_16x16x32_bf16 v[6:9], v[208:211], v[164:167], v[6:9]
	v_mfma_f32_16x16x32_bf16 v[2:5], v[216:219], v[164:167], v[2:5]
	s_setprio 0
	s_add_i32 s54, s54, 2
	s_add_u32 s24, s24, 0x100
	s_addc_u32 s25, s25, 0
	s_add_u32 s52, s52, 0x100
	s_addc_u32 s53, s53, 0
	s_cmp_gt_u32 s54, 29
	s_barrier
	s_cbranch_scc0 .LBB0_377
	s_branch .Lp2_loop_exit
.LBB0_377:
	s_add_u32 s26, s24, 0xfff80080
	s_addc_u32 s27, s25, -1
	s_cmp_eq_u32 s54, 28
	s_cselect_b32 s29, s17, s27
	s_cselect_b32 s28, s19, s26
	s_cselect_b32 s27, s15, s53
	s_cselect_b32 s26, s51, s52
	s_add_i32 m0, s39, 0xc000
	s_nop 0
	global_load_lds_dwordx4 v136, s[24:25]
	s_add_i32 m0, s39, 0xe000
	s_nop 0
	global_load_lds_dwordx4 v138, s[24:25]
	s_waitcnt vmcnt(10)
	s_barrier
	s_waitcnt lgkmcnt(0)
	s_setprio 1
	v_mfma_f32_16x16x32_bf16 v[126:129], v[152:155], v[172:175], v[126:129]
	ds_read_b128 v[204:207], v151
	v_mfma_f32_16x16x32_bf16 v[122:125], v[160:163], v[172:175], v[122:125]
	v_mfma_f32_16x16x32_bf16 v[118:121], v[152:155], v[180:183], v[118:121]
	v_mfma_f32_16x16x32_bf16 v[114:117], v[160:163], v[180:183], v[114:117]
	v_mfma_f32_16x16x32_bf16 v[102:105], v[152:155], v[188:191], v[102:105]
	ds_read_b128 v[208:211], v151 offset:1024
	v_mfma_f32_16x16x32_bf16 v[98:101], v[160:163], v[188:191], v[98:101]
	v_mfma_f32_16x16x32_bf16 v[86:89], v[152:155], v[196:199], v[86:89]
	v_mfma_f32_16x16x32_bf16 v[82:85], v[160:163], v[196:199], v[82:85]
	v_mfma_f32_16x16x32_bf16 v[126:129], v[156:159], v[176:179], v[126:129]
	ds_read_b128 v[212:215], v151 offset:2048
	v_mfma_f32_16x16x32_bf16 v[122:125], v[168:171], v[176:179], v[122:125]
	v_mfma_f32_16x16x32_bf16 v[118:121], v[156:159], v[184:187], v[118:121]
	v_mfma_f32_16x16x32_bf16 v[114:117], v[168:171], v[184:187], v[114:117]
	v_mfma_f32_16x16x32_bf16 v[102:105], v[156:159], v[192:195], v[102:105]
	ds_read_b128 v[216:219], v151 offset:3072
	v_mfma_f32_16x16x32_bf16 v[98:101], v[168:171], v[192:195], v[98:101]
	v_mfma_f32_16x16x32_bf16 v[86:89], v[156:159], v[200:203], v[86:89]
	v_mfma_f32_16x16x32_bf16 v[82:85], v[168:171], v[200:203], v[82:85]
	s_setprio 0
	s_barrier
	s_add_i32 s55, s47, s34
	s_add_u32 s96, s26, 0x80
	s_addc_u32 s97, s27, 0
	s_mov_b32 m0, s55
	s_nop 0
	global_load_lds_dwordx4 v130, s[26:27]
	s_add_i32 m0, s55, 0x2000
	s_nop 0
	global_load_lds_dwordx4 v132, s[26:27]
	s_waitcnt vmcnt(10)
	s_barrier
	s_waitcnt lgkmcnt(0)
	s_setprio 1
	v_mfma_f32_16x16x32_bf16 v[110:113], v[204:207], v[172:175], v[110:113]
	ds_read_b128 v[224:227], v150 offset:16384
	v_mfma_f32_16x16x32_bf16 v[106:109], v[212:215], v[172:175], v[106:109]
	v_mfma_f32_16x16x32_bf16 v[94:97], v[204:207], v[180:183], v[94:97]
	ds_read_b128 v[228:231], v150 offset:17408
	v_mfma_f32_16x16x32_bf16 v[90:93], v[212:215], v[180:183], v[90:93]
	v_mfma_f32_16x16x32_bf16 v[78:81], v[204:207], v[188:191], v[78:81]
	ds_read_b128 v[232:235], v150 offset:18432
	v_mfma_f32_16x16x32_bf16 v[74:77], v[212:215], v[188:191], v[74:77]
	v_mfma_f32_16x16x32_bf16 v[70:73], v[204:207], v[196:199], v[70:73]
	ds_read_b128 v[236:239], v150 offset:19456
	v_mfma_f32_16x16x32_bf16 v[66:69], v[212:215], v[196:199], v[66:69]
	v_mfma_f32_16x16x32_bf16 v[110:113], v[208:211], v[176:179], v[110:113]
	ds_read_b128 v[240:243], v150 offset:20480
	v_mfma_f32_16x16x32_bf16 v[106:109], v[216:219], v[176:179], v[106:109]
	v_mfma_f32_16x16x32_bf16 v[94:97], v[208:211], v[184:187], v[94:97]
	ds_read_b128 v[244:247], v150 offset:21504
	v_mfma_f32_16x16x32_bf16 v[90:93], v[216:219], v[184:187], v[90:93]
	v_mfma_f32_16x16x32_bf16 v[78:81], v[208:211], v[192:195], v[78:81]
	ds_read_b128 v[248:251], v150 offset:22528
	v_mfma_f32_16x16x32_bf16 v[74:77], v[216:219], v[192:195], v[74:77]
	v_mfma_f32_16x16x32_bf16 v[70:73], v[208:211], v[200:203], v[70:73]
	ds_read_b128 v[164:167], v150 offset:23552
	v_mfma_f32_16x16x32_bf16 v[66:69], v[216:219], v[200:203], v[66:69]
	s_setprio 0
	s_barrier
	s_mov_b32 m0, s39
	s_add_u32 s94, s28, 0x80
	s_addc_u32 s95, s29, 0
	global_load_lds_dwordx4 v130, s[28:29]
	s_mov_b32 m0, s40
	s_nop 0
	global_load_lds_dwordx4 v132, s[28:29]
	s_waitcnt vmcnt(8)
	s_barrier
	s_waitcnt lgkmcnt(0)
	s_setprio 1
	v_mfma_f32_16x16x32_bf16 v[62:65], v[152:155], v[224:227], v[62:65]
	ds_read_b128 v[172:175], v150 offset:32768
	v_mfma_f32_16x16x32_bf16 v[58:61], v[160:163], v[224:227], v[58:61]
	v_mfma_f32_16x16x32_bf16 v[54:57], v[152:155], v[232:235], v[54:57]
	ds_read_b128 v[176:179], v150 offset:33792
	v_mfma_f32_16x16x32_bf16 v[50:53], v[160:163], v[232:235], v[50:53]
	v_mfma_f32_16x16x32_bf16 v[38:41], v[152:155], v[240:243], v[38:41]
	ds_read_b128 v[180:183], v150 offset:34816
	v_mfma_f32_16x16x32_bf16 v[34:37], v[160:163], v[240:243], v[34:37]
	v_mfma_f32_16x16x32_bf16 v[22:25], v[152:155], v[248:251], v[22:25]
	ds_read_b128 v[184:187], v150 offset:35840
	v_mfma_f32_16x16x32_bf16 v[18:21], v[160:163], v[248:251], v[18:21]
	v_mfma_f32_16x16x32_bf16 v[62:65], v[156:159], v[228:231], v[62:65]
	ds_read_b128 v[188:191], v150 offset:36864
	v_mfma_f32_16x16x32_bf16 v[58:61], v[168:171], v[228:231], v[58:61]
	v_mfma_f32_16x16x32_bf16 v[54:57], v[156:159], v[236:239], v[54:57]
	ds_read_b128 v[192:195], v150 offset:37888
	v_mfma_f32_16x16x32_bf16 v[50:53], v[168:171], v[236:239], v[50:53]
	v_mfma_f32_16x16x32_bf16 v[38:41], v[156:159], v[244:247], v[38:41]
	ds_read_b128 v[196:199], v150 offset:38912
	v_mfma_f32_16x16x32_bf16 v[34:37], v[168:171], v[244:247], v[34:37]
	v_mfma_f32_16x16x32_bf16 v[22:25], v[156:159], v[164:167], v[22:25]
	ds_read_b128 v[200:203], v150 offset:39936
	v_mfma_f32_16x16x32_bf16 v[18:21], v[168:171], v[164:167], v[18:21]
	s_setprio 0
	s_barrier
	s_add_u32 s56, s26, 0x80000
	s_addc_u32 s57, s27, 0
	s_add_i32 s55, s48, s34
	s_mov_b32 m0, s55
	s_nop 0
	global_load_lds_dwordx4 v130, s[56:57]
	s_add_i32 m0, s55, 0x2000
	s_nop 0
	global_load_lds_dwordx4 v132, s[56:57]
	s_waitcnt vmcnt(10)
	s_barrier
	s_waitcnt lgkmcnt(0)
	s_setprio 1
	v_mfma_f32_16x16x32_bf16 v[46:49], v[204:207], v[224:227], v[46:49]
	ds_read_b128 v[152:155], v222
	v_mfma_f32_16x16x32_bf16 v[42:45], v[212:215], v[224:227], v[42:45]
	v_mfma_f32_16x16x32_bf16 v[30:33], v[204:207], v[232:235], v[30:33]
	v_mfma_f32_16x16x32_bf16 v[26:29], v[212:215], v[232:235], v[26:29]
	v_mfma_f32_16x16x32_bf16 v[14:17], v[204:207], v[240:243], v[14:17]
	ds_read_b128 v[156:159], v222 offset:1024
	v_mfma_f32_16x16x32_bf16 v[10:13], v[212:215], v[240:243], v[10:13]
	v_mfma_f32_16x16x32_bf16 v[6:9], v[204:207], v[248:251], v[6:9]
	v_mfma_f32_16x16x32_bf16 v[2:5], v[212:215], v[248:251], v[2:5]
	v_mfma_f32_16x16x32_bf16 v[46:49], v[208:211], v[228:231], v[46:49]
	ds_read_b128 v[160:163], v222 offset:2048
	v_mfma_f32_16x16x32_bf16 v[42:45], v[216:219], v[228:231], v[42:45]
	v_mfma_f32_16x16x32_bf16 v[30:33], v[208:211], v[236:239], v[30:33]
	v_mfma_f32_16x16x32_bf16 v[26:29], v[216:219], v[236:239], v[26:29]
	v_mfma_f32_16x16x32_bf16 v[14:17], v[208:211], v[244:247], v[14:17]
	ds_read_b128 v[168:171], v222 offset:3072
	v_mfma_f32_16x16x32_bf16 v[10:13], v[216:219], v[244:247], v[10:13]
	v_mfma_f32_16x16x32_bf16 v[6:9], v[208:211], v[164:167], v[6:9]
	v_mfma_f32_16x16x32_bf16 v[2:5], v[216:219], v[164:167], v[2:5]
	s_setprio 0
	s_barrier
	s_add_i32 s55, 0, 0x18000
	s_add_u32 s28, s28, 0x80000
	s_addc_u32 s29, s29, 0
	s_mov_b32 m0, s41
	s_nop 0
	global_load_lds_dwordx4 v130, s[28:29]
	s_mov_b32 m0, s42
	s_nop 0
	global_load_lds_dwordx4 v132, s[28:29]
	s_waitcnt vmcnt(10)
	s_barrier
	s_waitcnt lgkmcnt(0)
	s_setprio 1
	v_mfma_f32_16x16x32_bf16 v[126:129], v[152:155], v[172:175], v[126:129]
	ds_read_b128 v[204:207], v223
	v_mfma_f32_16x16x32_bf16 v[122:125], v[160:163], v[172:175], v[122:125]
	v_mfma_f32_16x16x32_bf16 v[118:121], v[152:155], v[180:183], v[118:121]
	v_mfma_f32_16x16x32_bf16 v[114:117], v[160:163], v[180:183], v[114:117]
	v_mfma_f32_16x16x32_bf16 v[102:105], v[152:155], v[188:191], v[102:105]
	ds_read_b128 v[208:211], v223 offset:1024
	v_mfma_f32_16x16x32_bf16 v[98:101], v[160:163], v[188:191], v[98:101]
	v_mfma_f32_16x16x32_bf16 v[86:89], v[152:155], v[196:199], v[86:89]
	v_mfma_f32_16x16x32_bf16 v[82:85], v[160:163], v[196:199], v[82:85]
	v_mfma_f32_16x16x32_bf16 v[126:129], v[156:159], v[176:179], v[126:129]
	ds_read_b128 v[212:215], v223 offset:2048
	v_mfma_f32_16x16x32_bf16 v[122:125], v[168:171], v[176:179], v[122:125]
	v_mfma_f32_16x16x32_bf16 v[118:121], v[156:159], v[184:187], v[118:121]
	v_mfma_f32_16x16x32_bf16 v[114:117], v[168:171], v[184:187], v[114:117]
	v_mfma_f32_16x16x32_bf16 v[102:105], v[156:159], v[192:195], v[102:105]
	ds_read_b128 v[216:219], v223 offset:3072
	v_mfma_f32_16x16x32_bf16 v[98:101], v[168:171], v[192:195], v[98:101]
	v_mfma_f32_16x16x32_bf16 v[86:89], v[156:159], v[200:203], v[86:89]
	v_mfma_f32_16x16x32_bf16 v[82:85], v[168:171], v[200:203], v[82:85]
	s_setprio 0
	s_barrier
	s_add_i32 s84, 0, 0x1c000
	s_add_i32 s85, s55, s34
	s_mov_b32 m0, s85
	s_nop 0
	global_load_lds_dwordx4 v130, s[96:97]
	s_add_i32 m0, s85, 0x2000
	s_nop 0
	global_load_lds_dwordx4 v132, s[96:97]
	s_waitcnt vmcnt(10)
	s_barrier
	s_waitcnt lgkmcnt(0)
	s_setprio 1
	v_mfma_f32_16x16x32_bf16 v[110:113], v[204:207], v[172:175], v[110:113]
	ds_read_b128 v[224:227], v150 offset:49152
	v_mfma_f32_16x16x32_bf16 v[106:109], v[212:215], v[172:175], v[106:109]
	v_mfma_f32_16x16x32_bf16 v[94:97], v[204:207], v[180:183], v[94:97]
	ds_read_b128 v[228:231], v150 offset:50176
	v_mfma_f32_16x16x32_bf16 v[90:93], v[212:215], v[180:183], v[90:93]
	v_mfma_f32_16x16x32_bf16 v[78:81], v[204:207], v[188:191], v[78:81]
	ds_read_b128 v[232:235], v150 offset:51200
	v_mfma_f32_16x16x32_bf16 v[74:77], v[212:215], v[188:191], v[74:77]
	v_mfma_f32_16x16x32_bf16 v[70:73], v[204:207], v[196:199], v[70:73]
	ds_read_b128 v[236:239], v150 offset:52224
	v_mfma_f32_16x16x32_bf16 v[66:69], v[212:215], v[196:199], v[66:69]
	v_mfma_f32_16x16x32_bf16 v[110:113], v[208:211], v[176:179], v[110:113]
	ds_read_b128 v[240:243], v150 offset:53248
	v_mfma_f32_16x16x32_bf16 v[106:109], v[216:219], v[176:179], v[106:109]
	v_mfma_f32_16x16x32_bf16 v[94:97], v[208:211], v[184:187], v[94:97]
	ds_read_b128 v[244:247], v150 offset:54272
	v_mfma_f32_16x16x32_bf16 v[90:93], v[216:219], v[184:187], v[90:93]
	v_mfma_f32_16x16x32_bf16 v[78:81], v[208:211], v[192:195], v[78:81]
	ds_read_b128 v[248:251], v150 offset:55296
	v_mfma_f32_16x16x32_bf16 v[74:77], v[216:219], v[192:195], v[74:77]
	v_mfma_f32_16x16x32_bf16 v[70:73], v[208:211], v[200:203], v[70:73]
	ds_read_b128 v[164:167], v150 offset:56320
	v_mfma_f32_16x16x32_bf16 v[66:69], v[216:219], v[200:203], v[66:69]
	s_setprio 0
	s_barrier
	s_mov_b32 m0, s45
	s_nop 0
	global_load_lds_dwordx4 v130, s[94:95]
	s_mov_b32 m0, s46
	s_nop 0
	global_load_lds_dwordx4 v132, s[94:95]
	s_waitcnt vmcnt(8)
	s_barrier
	s_waitcnt lgkmcnt(0)
	s_setprio 1
	v_mfma_f32_16x16x32_bf16 v[62:65], v[152:155], v[224:227], v[62:65]
	ds_read_b128 v[172:175], v150
	v_mfma_f32_16x16x32_bf16 v[58:61], v[160:163], v[224:227], v[58:61]
	v_mfma_f32_16x16x32_bf16 v[54:57], v[152:155], v[232:235], v[54:57]
	ds_read_b128 v[176:179], v150 offset:1024
	v_mfma_f32_16x16x32_bf16 v[50:53], v[160:163], v[232:235], v[50:53]
	v_mfma_f32_16x16x32_bf16 v[38:41], v[152:155], v[240:243], v[38:41]
	ds_read_b128 v[180:183], v150 offset:2048
	v_mfma_f32_16x16x32_bf16 v[34:37], v[160:163], v[240:243], v[34:37]
	v_mfma_f32_16x16x32_bf16 v[22:25], v[152:155], v[248:251], v[22:25]
	ds_read_b128 v[184:187], v150 offset:3072
	v_mfma_f32_16x16x32_bf16 v[18:21], v[160:163], v[248:251], v[18:21]
	v_mfma_f32_16x16x32_bf16 v[62:65], v[156:159], v[228:231], v[62:65]
	ds_read_b128 v[188:191], v150 offset:4096
	v_mfma_f32_16x16x32_bf16 v[58:61], v[168:171], v[228:231], v[58:61]
	v_mfma_f32_16x16x32_bf16 v[54:57], v[156:159], v[236:239], v[54:57]
	ds_read_b128 v[192:195], v150 offset:5120
	v_mfma_f32_16x16x32_bf16 v[50:53], v[168:171], v[236:239], v[50:53]
	v_mfma_f32_16x16x32_bf16 v[38:41], v[156:159], v[244:247], v[38:41]
	ds_read_b128 v[196:199], v150 offset:6144
	v_mfma_f32_16x16x32_bf16 v[34:37], v[168:171], v[244:247], v[34:37]
	v_mfma_f32_16x16x32_bf16 v[22:25], v[156:159], v[164:167], v[22:25]
	ds_read_b128 v[200:203], v150 offset:7168
	v_mfma_f32_16x16x32_bf16 v[18:21], v[168:171], v[164:167], v[18:21]
	s_setprio 0
	s_barrier
	s_add_u32 s26, s26, 0x80080
	s_addc_u32 s27, s27, 0
	s_add_i32 s84, s84, s34
	s_mov_b32 m0, s84
	s_nop 0
	global_load_lds_dwordx4 v130, s[26:27]
	s_add_i32 m0, s84, 0x2000
	s_nop 0
	global_load_lds_dwordx4 v132, s[26:27]
	s_waitcnt vmcnt(10)
	s_barrier
	s_waitcnt lgkmcnt(0)
	s_setprio 1
	v_mfma_f32_16x16x32_bf16 v[46:49], v[204:207], v[224:227], v[46:49]
	ds_read_b128 v[152:155], v149
	v_mfma_f32_16x16x32_bf16 v[42:45], v[212:215], v[224:227], v[42:45]
	v_mfma_f32_16x16x32_bf16 v[30:33], v[204:207], v[232:235], v[30:33]
	v_mfma_f32_16x16x32_bf16 v[26:29], v[212:215], v[232:235], v[26:29]
	v_mfma_f32_16x16x32_bf16 v[14:17], v[204:207], v[240:243], v[14:17]
	ds_read_b128 v[156:159], v149 offset:1024
	v_mfma_f32_16x16x32_bf16 v[10:13], v[212:215], v[240:243], v[10:13]
	v_mfma_f32_16x16x32_bf16 v[6:9], v[204:207], v[248:251], v[6:9]
	v_mfma_f32_16x16x32_bf16 v[2:5], v[212:215], v[248:251], v[2:5]
	v_mfma_f32_16x16x32_bf16 v[46:49], v[208:211], v[228:231], v[46:49]
	ds_read_b128 v[160:163], v149 offset:2048
	v_mfma_f32_16x16x32_bf16 v[42:45], v[216:219], v[228:231], v[42:45]
	v_mfma_f32_16x16x32_bf16 v[30:33], v[208:211], v[236:239], v[30:33]
	v_mfma_f32_16x16x32_bf16 v[26:29], v[216:219], v[236:239], v[26:29]
	v_mfma_f32_16x16x32_bf16 v[14:17], v[208:211], v[244:247], v[14:17]
	ds_read_b128 v[168:171], v149 offset:3072
	v_mfma_f32_16x16x32_bf16 v[10:13], v[216:219], v[244:247], v[10:13]
	v_mfma_f32_16x16x32_bf16 v[6:9], v[208:211], v[164:167], v[6:9]
	v_mfma_f32_16x16x32_bf16 v[2:5], v[216:219], v[164:167], v[2:5]
	s_setprio 0
	s_add_i32 s54, s54, 2
	s_add_u32 s24, s24, 0x100
	s_addc_u32 s25, s25, 0
	s_add_u32 s52, s52, 0x100
	s_addc_u32 s53, s53, 0
	s_cmp_gt_u32 s54, 29
	s_barrier
	s_cbranch_scc0 .LBB0_377
